# hgrn_sample state loads hoisted above the q/g/v wait; attention head loop z/next-q loads issued at start of PV
# speedup vs baseline: 1.0057x; 1.0057x over previous
.LBB0_324:
	v_mov_b32_e32 v0, 0
	v_readlane_b32 s2, v254, 7
	v_mbcnt_lo_u32_b32 v0, -1, v0
	v_mbcnt_hi_u32_b32 v82, -1, v0
	v_add_u32_e32 v68, s2, v82
	s_ashr_i32 s2, s0, 4
	s_add_i32 s6, s2, 0x4000
	s_ashr_i32 s7, s6, 31
	s_add_u32 s2, s6, s14
	s_addc_u32 s3, s7, 0
	s_lshl_b64 s[2:3], s[2:3], 8
	s_add_u32 s8, s16, s2
	s_addc_u32 s9, s17, s3
	v_cmp_gt_i32_e64 s[2:3], s1, v68
	v_ashrrev_i32_e32 v69, 31, v68
	v_lshl_add_u32 v83, v68, 2, s91
	s_waitcnt vmcnt(63) expcnt(7) lgkmcnt(15)
	s_barrier
	v_readlane_b32 s22, v254, 15
	v_readlane_b32 s23, v254, 16
	s_load_dwordx2 s[12:13], s[22:23], 0x20
	v_ashrrev_i32_e32 v141, 5, v68
	v_lshlrev_b32_e32 v0, 4, v82
	v_and_b32_e32 v6, 0x1f0, v0
	v_lshlrev_b32_e32 v0, 7, v141
	v_ashrrev_i32_e32 v1, 31, v0
	v_add_u32_e32 v4, 0x400, v0
	v_lshlrev_b64 v[36:37], 2, v[0:1]
	v_ashrrev_i32_e32 v5, 31, v4
	v_or_b32_e32 v36, v36, v6
	v_lshlrev_b64 v[38:39], 2, v[4:5]
	s_waitcnt lgkmcnt(0)
	v_lshl_add_u64 v[2:3], s[12:13], 0, v[36:37]
	v_or_b32_e32 v38, v38, v6
	v_lshl_add_u64 v[2:3], v[2:3], 0, s[4:5]
	v_lshl_add_u64 v[4:5], s[12:13], 0, v[38:39]
	v_lshl_add_u64 v[4:5], v[4:5], 0, s[4:5]
	global_load_dwordx4 v[24:27], v[2:3], off nt
	global_load_dwordx4 v[20:23], v[4:5], off nt
	v_add_u32_e32 v2, 0x800, v0
	v_ashrrev_i32_e32 v3, 31, v2
	v_add_u32_e32 v4, 0xc00, v0
	v_lshlrev_b64 v[70:71], 2, v[2:3]
	v_ashrrev_i32_e32 v5, 31, v4
	v_or_b32_e32 v70, v70, v6
	v_lshlrev_b64 v[72:73], 2, v[4:5]
	v_lshl_add_u64 v[2:3], s[12:13], 0, v[70:71]
	v_or_b32_e32 v72, v72, v6
	v_lshl_add_u64 v[2:3], v[2:3], 0, s[4:5]
	v_lshl_add_u64 v[4:5], s[12:13], 0, v[72:73]
	v_lshl_add_u64 v[4:5], v[4:5], 0, s[4:5]
	global_load_dwordx4 v[32:35], v[2:3], off nt
	global_load_dwordx4 v[28:31], v[4:5], off nt
	v_add_u32_e32 v2, 0x1000, v0
	v_ashrrev_i32_e32 v3, 31, v2
	v_add_u32_e32 v4, 0x1400, v0
	v_lshlrev_b64 v[74:75], 2, v[2:3]
	v_ashrrev_i32_e32 v5, 31, v4
	v_or_b32_e32 v74, v74, v6
	v_lshlrev_b64 v[76:77], 2, v[4:5]
	v_lshl_add_u64 v[2:3], s[12:13], 0, v[74:75]
	v_or_b32_e32 v76, v76, v6
	v_lshl_add_u64 v[2:3], v[2:3], 0, s[4:5]
	v_lshl_add_u64 v[4:5], s[12:13], 0, v[76:77]
	v_lshl_add_u64 v[4:5], v[4:5], 0, s[4:5]
	global_load_dwordx4 v[44:47], v[2:3], off nt
	global_load_dwordx4 v[40:43], v[4:5], off nt
	v_add_u32_e32 v2, 0x1800, v0
	v_ashrrev_i32_e32 v3, 31, v2
	v_add_u32_e32 v4, 0x1c00, v0
	v_lshlrev_b64 v[78:79], 2, v[2:3]
	v_ashrrev_i32_e32 v5, 31, v4
	v_or_b32_e32 v78, v78, v6
	v_lshlrev_b64 v[84:85], 2, v[4:5]
	v_lshl_add_u64 v[2:3], s[12:13], 0, v[78:79]
	v_or_b32_e32 v84, v84, v6
	v_lshl_add_u64 v[2:3], v[2:3], 0, s[4:5]
	v_lshl_add_u64 v[4:5], s[12:13], 0, v[84:85]
	v_lshl_add_u64 v[4:5], v[4:5], 0, s[4:5]
	global_load_dwordx4 v[52:55], v[2:3], off nt
	global_load_dwordx4 v[48:51], v[4:5], off nt
	v_add_u32_e32 v2, 0x2000, v0
	v_ashrrev_i32_e32 v3, 31, v2
	v_add_u32_e32 v4, 0x2400, v0
	v_lshlrev_b64 v[86:87], 2, v[2:3]
	v_ashrrev_i32_e32 v5, 31, v4
	v_or_b32_e32 v86, v86, v6
	v_lshlrev_b64 v[88:89], 2, v[4:5]
	v_lshl_add_u64 v[2:3], s[12:13], 0, v[86:87]
	v_or_b32_e32 v88, v88, v6
	v_lshl_add_u64 v[2:3], v[2:3], 0, s[4:5]
	v_lshl_add_u64 v[4:5], s[12:13], 0, v[88:89]
	v_lshl_add_u64 v[4:5], v[4:5], 0, s[4:5]
	global_load_dwordx4 v[60:63], v[2:3], off nt
	global_load_dwordx4 v[56:59], v[4:5], off nt
	v_add_u32_e32 v2, 0x2800, v0
	v_ashrrev_i32_e32 v3, 31, v2
	v_add_u32_e32 v4, 0x2c00, v0
	v_lshlrev_b64 v[90:91], 2, v[2:3]
	v_ashrrev_i32_e32 v5, 31, v4
	v_or_b32_e32 v90, v90, v6
	v_lshlrev_b64 v[92:93], 2, v[4:5]
	v_lshl_add_u64 v[2:3], s[12:13], 0, v[90:91]
	v_or_b32_e32 v92, v92, v6
	v_lshl_add_u64 v[2:3], v[2:3], 0, s[4:5]
	v_lshl_add_u64 v[4:5], s[12:13], 0, v[92:93]
	v_lshl_add_u64 v[4:5], v[4:5], 0, s[4:5]
	global_load_dwordx4 v[64:67], v[2:3], off nt
	global_load_dwordx4 v[16:19], v[4:5], off nt
	v_add_u32_e32 v2, 0x3000, v0
	v_ashrrev_i32_e32 v3, 31, v2
	v_add_u32_e32 v4, 0x3400, v0
	v_lshlrev_b64 v[94:95], 2, v[2:3]
	v_ashrrev_i32_e32 v5, 31, v4
	v_or_b32_e32 v94, v94, v6
	v_lshlrev_b64 v[96:97], 2, v[4:5]
	v_lshl_add_u64 v[2:3], s[12:13], 0, v[94:95]
	v_or_b32_e32 v96, v96, v6
	v_lshl_add_u64 v[2:3], v[2:3], 0, s[4:5]
	v_lshl_add_u64 v[4:5], s[12:13], 0, v[96:97]
	v_lshl_add_u64 v[4:5], v[4:5], 0, s[4:5]
	global_load_dwordx4 v[12:15], v[2:3], off nt
	global_load_dwordx4 v[8:11], v[4:5], off nt
	v_add_u32_e32 v2, 0x3800, v0
	v_ashrrev_i32_e32 v3, 31, v2
	v_add_u32_e32 v0, 0x3c00, v0
	v_lshlrev_b64 v[98:99], 2, v[2:3]
	v_ashrrev_i32_e32 v1, 31, v0
	v_or_b32_e32 v98, v98, v6
	v_lshlrev_b64 v[102:103], 2, v[0:1]
	v_lshl_add_u64 v[2:3], s[12:13], 0, v[98:99]
	v_or_b32_e32 v102, v102, v6
	v_lshl_add_u64 v[100:101], v[2:3], 0, s[4:5]
	v_lshl_add_u64 v[0:1], s[12:13], 0, v[102:103]
	v_add_u32_e32 v152, s91, v6
	v_lshl_add_u64 v[104:105], v[0:1], 0, s[4:5]
	global_load_dwordx4 v[4:7], v[100:101], off nt
	global_load_dwordx4 v[0:3], v[104:105], off nt
	s_and_saveexec_b64 s[10:11], s[2:3]
	s_cbranch_execz .LBB0_326
	v_lshl_add_u64 v[176:177], v[68:69], 1, s[8:9]
	v_add_co_u32_e32 v178, vcc, 0x4080000, v176
	s_nop 1
	v_addc_co_u32_e32 v179, vcc, 0, v177, vcc
	global_load_ushort v180, v[178:179], off
	v_add_co_u32_e32 v178, vcc, 0x8100000, v176
	s_nop 1
	v_addc_co_u32_e32 v179, vcc, 0, v177, vcc
	global_load_ushort v181, v[178:179], off
	global_load_ushort v182, v[176:177], off
	s_waitcnt vmcnt(2)
	v_lshlrev_b32_e32 v176, 16, v180
	v_mul_f32_e32 v176, 0x3fb8aa3b, v176
	v_exp_f32_e32 v176, v176
	s_waitcnt vmcnt(0)
	v_lshlrev_b32_e32 v177, 16, v182
	ds_write2st64_b32 v83, v177, v176 offset1:2
	v_sub_f32_e32 v176, 1.0, v176
	v_lshlrev_b32_e32 v177, 16, v181
	ds_write2st64_b32 v83, v176, v177 offset0:4 offset1:6
.LBB0_326:
	s_or_b64 exec, exec, s[10:11]
	v_readlane_b32 s10, v254, 15
	v_readlane_b32 s11, v254, 16
	s_waitcnt lgkmcnt(0)
	s_barrier
	s_load_dwordx2 s[10:11], s[10:11], 0xa0
	s_waitcnt lgkmcnt(0)
	v_lshl_add_u64 v[36:37], s[10:11], 0, v[36:37]
	v_lshl_add_u64 v[106:107], v[36:37], 0, s[4:5]
	v_lshl_add_u64 v[36:37], s[10:11], 0, v[38:39]
	v_lshl_add_u64 v[110:111], v[36:37], 0, s[4:5]
	v_lshl_add_u64 v[36:37], s[10:11], 0, v[70:71]
	v_lshl_add_u64 v[118:119], v[36:37], 0, s[4:5]
	v_lshl_add_u64 v[36:37], s[10:11], 0, v[72:73]
	v_lshl_add_u64 v[120:121], v[36:37], 0, s[4:5]
	v_lshl_add_u64 v[36:37], s[10:11], 0, v[74:75]
	v_lshl_add_u64 v[128:129], v[36:37], 0, s[4:5]
	v_lshl_add_u64 v[36:37], s[10:11], 0, v[76:77]
	v_lshl_add_u64 v[130:131], v[36:37], 0, s[4:5]
	v_lshl_add_u64 v[36:37], s[10:11], 0, v[78:79]
	v_lshl_add_u64 v[138:139], v[36:37], 0, s[4:5]
	v_lshl_add_u64 v[36:37], s[10:11], 0, v[84:85]
	v_lshl_add_u64 v[84:85], v[36:37], 0, s[4:5]
	v_lshl_add_u64 v[36:37], s[10:11], 0, v[86:87]
	v_lshl_add_u64 v[86:87], v[36:37], 0, s[4:5]
	v_lshl_add_u64 v[36:37], s[10:11], 0, v[88:89]
	v_lshl_add_u64 v[88:89], v[36:37], 0, s[4:5]
	v_lshl_add_u64 v[36:37], s[10:11], 0, v[90:91]
	v_lshl_add_u64 v[90:91], v[36:37], 0, s[4:5]
	v_lshl_add_u64 v[36:37], s[10:11], 0, v[92:93]
	v_lshl_add_u32 v161, v141, 2, s91
	v_lshl_add_u64 v[92:93], v[36:37], 0, s[4:5]
	v_lshl_add_u64 v[36:37], s[10:11], 0, v[94:95]
	v_add_u32_e32 v171, 0x400, v161
	v_lshl_add_u64 v[76:77], v[36:37], 0, s[4:5]
	v_lshl_add_u64 v[36:37], s[10:11], 0, v[96:97]
	ds_read2_b32 v[100:101], v161 offset0:128 offset1:136
	ds_read2_b32 v[104:105], v171 offset1:8
	ds_read2_b32 v[108:109], v161 offset1:8
	ds_read2_b32 v[112:113], v161 offset0:144 offset1:152
	ds_read2_b32 v[114:115], v171 offset0:16 offset1:24
	ds_read2_b32 v[116:117], v161 offset0:16 offset1:24
	ds_read2_b32 v[122:123], v161 offset0:160 offset1:168
	ds_read2_b32 v[124:125], v171 offset0:32 offset1:40
	ds_read2_b32 v[126:127], v161 offset0:32 offset1:40
	ds_read2_b32 v[132:133], v161 offset0:176 offset1:184
	ds_read2_b32 v[134:135], v171 offset0:48 offset1:56
	ds_read2_b32 v[136:137], v161 offset0:48 offset1:56
	ds_read2_b32 v[142:143], v161 offset0:192 offset1:200
	ds_read2_b32 v[144:145], v171 offset0:64 offset1:72
	ds_read2_b32 v[146:147], v161 offset0:64 offset1:72
	ds_read2_b32 v[148:149], v161 offset0:208 offset1:216
	ds_read2_b32 v[150:151], v171 offset0:80 offset1:88
	ds_read2_b32 v[78:79], v161 offset0:80 offset1:88
	v_lshl_add_u64 v[74:75], v[36:37], 0, s[4:5]
	ds_read_b128 v[36:39], v152 offset:1536
	v_lshl_add_u64 v[70:71], s[10:11], 0, v[98:99]
	v_lshl_add_u64 v[72:73], v[70:71], 0, s[4:5]
	v_lshl_add_u64 v[70:71], s[10:11], 0, v[102:103]
	s_waitcnt lgkmcnt(14)
	v_mov_b32_e32 v102, v105
	s_waitcnt lgkmcnt(0)
	v_pk_mul_f32 v[94:95], v[36:37], v[104:105] op_sel_hi:[1,0]
	v_pk_mul_f32 v[104:105], v[38:39], v[104:105] op_sel_hi:[1,0]
	v_mov_b32_e32 v140, v133
	v_lshl_add_u32 v133, v141, 9, v152
	s_waitcnt vmcnt(15)
	v_pk_fma_f32 v[24:25], v[24:25], v[100:101], v[94:95] op_sel_hi:[1,0,1]
	v_mov_b32_e32 v94, v101
	v_pk_mul_f32 v[152:153], v[36:37], v[102:103] op_sel_hi:[1,0]
	v_pk_fma_f32 v[26:27], v[26:27], v[100:101], v[104:105] op_sel_hi:[1,0,1]
	v_pk_mul_f32 v[102:103], v[38:39], v[102:103] op_sel_hi:[1,0]
	s_waitcnt vmcnt(14)
	v_pk_fma_f32 v[20:21], v[20:21], v[94:95], v[152:153] op_sel_hi:[1,0,1]
	v_mov_b32_e32 v152, v109
	v_pk_mul_f32 v[154:155], v[36:37], v[114:115] op_sel_hi:[1,0]
	v_pk_fma_f32 v[100:101], v[108:109], v[26:27], 0 op_sel_hi:[0,1,0]
	v_pk_fma_f32 v[22:23], v[22:23], v[94:95], v[102:103] op_sel_hi:[1,0,1]
	s_waitcnt vmcnt(13)
	v_pk_fma_f32 v[32:33], v[32:33], v[112:113], v[154:155] op_sel_hi:[1,0,1]
	v_mov_b32_e32 v154, v115
	v_pk_fma_f32 v[94:95], v[152:153], v[22:23], v[100:101] op_sel_hi:[0,1,1]
	v_pk_mul_f32 v[100:101], v[38:39], v[114:115] op_sel_hi:[1,0]
	v_mov_b32_e32 v96, v113
	v_pk_mul_f32 v[156:157], v[36:37], v[154:155] op_sel_hi:[1,0]
	v_pk_fma_f32 v[34:35], v[34:35], v[112:113], v[100:101] op_sel_hi:[1,0,1]
	v_pk_mul_f32 v[100:101], v[38:39], v[154:155] op_sel_hi:[1,0]
	s_waitcnt vmcnt(12)
	v_pk_fma_f32 v[28:29], v[28:29], v[96:97], v[156:157] op_sel_hi:[1,0,1]
	v_pk_mul_f32 v[158:159], v[36:37], v[124:125] op_sel_hi:[1,0]
	v_mov_b32_e32 v160, v125
	v_pk_fma_f32 v[30:31], v[30:31], v[96:97], v[100:101] op_sel_hi:[1,0,1]
	v_pk_mul_f32 v[96:97], v[38:39], v[124:125] op_sel_hi:[1,0]
	s_waitcnt vmcnt(11)
	v_pk_fma_f32 v[44:45], v[44:45], v[122:123], v[158:159] op_sel_hi:[1,0,1]
	v_mov_b32_e32 v158, v123
	v_pk_mul_f32 v[164:165], v[36:37], v[134:135] op_sel_hi:[1,0]
	v_pk_fma_f32 v[46:47], v[46:47], v[122:123], v[96:97] op_sel_hi:[1,0,1]
	v_pk_mul_f32 v[96:97], v[38:39], v[160:161] op_sel_hi:[1,0]
	s_waitcnt vmcnt(9)
	v_pk_fma_f32 v[52:53], v[52:53], v[132:133], v[164:165] op_sel_hi:[1,0,1]
	v_mov_b32_e32 v164, v135
	v_pk_fma_f32 v[42:43], v[42:43], v[158:159], v[96:97] op_sel_hi:[1,0,1]
	v_pk_mul_f32 v[96:97], v[38:39], v[134:135] op_sel_hi:[1,0]
	v_pk_mul_f32 v[168:169], v[36:37], v[144:145] op_sel_hi:[1,0]
	v_pk_fma_f32 v[54:55], v[54:55], v[132:133], v[96:97] op_sel_hi:[1,0,1]
	v_pk_mul_f32 v[96:97], v[38:39], v[164:165] op_sel_hi:[1,0]
	v_mov_b32_e32 v170, v145
	s_waitcnt vmcnt(8)
	v_pk_fma_f32 v[50:51], v[50:51], v[140:141], v[96:97] op_sel_hi:[1,0,1]
	v_pk_mul_f32 v[96:97], v[38:39], v[144:145] op_sel_hi:[1,0]
	s_waitcnt vmcnt(7)
	v_pk_fma_f32 v[60:61], v[60:61], v[142:143], v[168:169] op_sel_hi:[1,0,1]
	v_mov_b32_e32 v168, v143
	v_pk_fma_f32 v[62:63], v[62:63], v[142:143], v[96:97] op_sel_hi:[1,0,1]
	v_pk_mul_f32 v[96:97], v[38:39], v[170:171] op_sel_hi:[1,0]
	v_pk_fma_f32 v[98:99], v[108:109], v[24:25], 0 op_sel_hi:[0,1,0]
	s_waitcnt vmcnt(6)
	v_pk_fma_f32 v[58:59], v[58:59], v[168:169], v[96:97] op_sel_hi:[1,0,1]
	v_pk_mul_f32 v[96:97], v[38:39], v[150:151] op_sel_hi:[1,0]
	v_pk_fma_f32 v[98:99], v[152:153], v[20:21], v[98:99] op_sel_hi:[0,1,1]
	s_waitcnt vmcnt(5)
	v_pk_fma_f32 v[66:67], v[66:67], v[148:149], v[96:97] op_sel_hi:[1,0,1]
	v_add_co_u32_e32 v96, vcc, s20, v106
	v_pk_mul_f32 v[162:163], v[36:37], v[160:161] op_sel_hi:[1,0]
	s_nop 0
	v_addc_co_u32_e32 v97, vcc, 0, v107, vcc
	global_store_dwordx4 v[96:97], v[24:27], off nt
	v_pk_fma_f32 v[40:41], v[40:41], v[158:159], v[162:163] op_sel_hi:[1,0,1]
	v_pk_mul_f32 v[166:167], v[36:37], v[164:165] op_sel_hi:[1,0]
	v_add_co_u32_e32 v24, vcc, s20, v110
	v_pk_fma_f32 v[48:49], v[48:49], v[140:141], v[166:167] op_sel_hi:[1,0,1]
	s_nop 0
	v_addc_co_u32_e32 v25, vcc, 0, v111, vcc
	global_store_dwordx4 v[24:25], v[20:23], off nt
	v_pk_mul_f32 v[172:173], v[36:37], v[170:171] op_sel_hi:[1,0]
	v_pk_mul_f32 v[174:175], v[36:37], v[150:151] op_sel_hi:[1,0]
	v_add_co_u32_e32 v20, vcc, s20, v118
	v_pk_fma_f32 v[56:57], v[56:57], v[168:169], v[172:173] op_sel_hi:[1,0,1]
	s_nop 0
	v_addc_co_u32_e32 v21, vcc, 0, v119, vcc
	global_store_dwordx4 v[20:21], v[32:35], off nt
	v_add_co_u32_e32 v20, vcc, s20, v120
	v_pk_fma_f32 v[98:99], v[116:117], v[32:33], v[98:99] op_sel_hi:[0,1,1]
	s_nop 0
	v_addc_co_u32_e32 v21, vcc, 0, v121, vcc
	global_store_dwordx4 v[20:21], v[28:31], off nt
	v_add_co_u32_e32 v20, vcc, s20, v128
	v_mov_b32_e32 v156, v117
	s_nop 0
	v_addc_co_u32_e32 v21, vcc, 0, v129, vcc
	global_store_dwordx4 v[20:21], v[44:47], off nt
	v_add_co_u32_e32 v20, vcc, s20, v130
	v_pk_fma_f32 v[64:65], v[64:65], v[148:149], v[174:175] op_sel_hi:[1,0,1]
	s_nop 0
	v_addc_co_u32_e32 v21, vcc, 0, v131, vcc
	global_store_dwordx4 v[20:21], v[40:43], off nt
	v_add_co_u32_e32 v20, vcc, s20, v138
	v_pk_fma_f32 v[94:95], v[116:117], v[34:35], v[94:95] op_sel_hi:[0,1,1]
	s_nop 0
	v_addc_co_u32_e32 v21, vcc, 0, v139, vcc
	global_store_dwordx4 v[20:21], v[52:55], off nt
	v_add_co_u32_e32 v20, vcc, s20, v84
	v_mov_b32_e32 v22, v151
	s_nop 0
	v_addc_co_u32_e32 v21, vcc, 0, v85, vcc
	global_store_dwordx4 v[20:21], v[48:51], off nt
	v_add_co_u32_e32 v20, vcc, s20, v86
	v_pk_fma_f32 v[98:99], v[156:157], v[28:29], v[98:99] op_sel_hi:[0,1,1]
	s_nop 0
	v_addc_co_u32_e32 v21, vcc, 0, v87, vcc
	global_store_dwordx4 v[20:21], v[60:63], off nt
	v_add_co_u32_e32 v20, vcc, s20, v88
	v_pk_fma_f32 v[94:95], v[156:157], v[30:31], v[94:95] op_sel_hi:[0,1,1]
	s_nop 0
	v_addc_co_u32_e32 v21, vcc, 0, v89, vcc
	global_store_dwordx4 v[20:21], v[56:59], off nt
	v_add_co_u32_e32 v20, vcc, s20, v90
	v_pk_mul_f32 v[24:25], v[36:37], v[22:23] op_sel_hi:[1,0]
	s_nop 0
	v_addc_co_u32_e32 v21, vcc, 0, v91, vcc
	global_store_dwordx4 v[20:21], v[64:67], off nt
	v_mov_b32_e32 v20, v149
	v_pk_mul_f32 v[22:23], v[38:39], v[22:23] op_sel_hi:[1,0]
	v_pk_fma_f32 v[98:99], v[126:127], v[44:45], v[98:99] op_sel_hi:[0,1,1]
	v_mov_b32_e32 v162, v127
	v_pk_fma_f32 v[94:95], v[126:127], v[46:47], v[94:95] op_sel_hi:[0,1,1]
	s_waitcnt vmcnt(15)
	v_pk_fma_f32 v[16:17], v[16:17], v[20:21], v[24:25] op_sel_hi:[1,0,1]
	v_pk_fma_f32 v[18:19], v[18:19], v[20:21], v[22:23] op_sel_hi:[1,0,1]
	v_add_co_u32_e32 v20, vcc, s20, v92
	v_pk_fma_f32 v[98:99], v[162:163], v[40:41], v[98:99] op_sel_hi:[0,1,1]
	v_pk_fma_f32 v[94:95], v[162:163], v[42:43], v[94:95] op_sel_hi:[0,1,1]
	v_addc_co_u32_e32 v21, vcc, 0, v93, vcc
	v_pk_fma_f32 v[98:99], v[136:137], v[52:53], v[98:99] op_sel_hi:[0,1,1]
	v_mov_b32_e32 v166, v137
	v_pk_fma_f32 v[94:95], v[136:137], v[54:55], v[94:95] op_sel_hi:[0,1,1]
	global_store_dwordx4 v[20:21], v[16:19], off nt
	v_pk_fma_f32 v[98:99], v[166:167], v[48:49], v[98:99] op_sel_hi:[0,1,1]
	v_pk_fma_f32 v[94:95], v[166:167], v[50:51], v[94:95] op_sel_hi:[0,1,1]
	ds_read2_b32 v[20:21], v161 offset0:96 offset1:104
	ds_read2_b32 v[22:23], v171 offset0:96 offset1:104
	ds_read2_b32 v[24:25], v161 offset0:224 offset1:232
	v_pk_fma_f32 v[98:99], v[146:147], v[60:61], v[98:99] op_sel_hi:[0,1,1]
	v_mov_b32_e32 v172, v147
	v_pk_fma_f32 v[94:95], v[146:147], v[62:63], v[94:95] op_sel_hi:[0,1,1]
	v_pk_fma_f32 v[98:99], v[172:173], v[56:57], v[98:99] op_sel_hi:[0,1,1]
	v_pk_fma_f32 v[94:95], v[172:173], v[58:59], v[94:95] op_sel_hi:[0,1,1]
	v_pk_fma_f32 v[98:99], v[78:79], v[64:65], v[98:99] op_sel_hi:[0,1,1]
	v_pk_fma_f32 v[94:95], v[78:79], v[66:67], v[94:95] op_sel_hi:[0,1,1]
	v_mov_b32_e32 v26, v79
	v_pk_fma_f32 v[16:17], v[26:27], v[16:17], v[98:99] op_sel_hi:[0,1,1]
	v_pk_fma_f32 v[18:19], v[26:27], v[18:19], v[94:95] op_sel_hi:[0,1,1]
	s_waitcnt lgkmcnt(1)
	v_pk_mul_f32 v[26:27], v[36:37], v[22:23] op_sel_hi:[1,0]
	v_lshl_add_u64 v[70:71], v[70:71], 0, s[4:5]
	s_waitcnt vmcnt(15) lgkmcnt(0)
	v_pk_fma_f32 v[12:13], v[12:13], v[24:25], v[26:27] op_sel_hi:[1,0,1]
	v_pk_mul_f32 v[26:27], v[38:39], v[22:23] op_sel_hi:[1,0]
	s_nop 0
	v_pk_fma_f32 v[14:15], v[14:15], v[24:25], v[26:27] op_sel_hi:[1,0,1]
	v_add_co_u32_e32 v26, vcc, s20, v76
	s_nop 1
	v_addc_co_u32_e32 v27, vcc, 0, v77, vcc
	global_store_dwordx4 v[26:27], v[12:15], off nt
	s_nop 1
	v_pk_fma_f32 v[14:15], v[20:21], v[14:15], v[18:19] op_sel_hi:[0,1,1]
	v_mov_b32_e32 v18, v23
	v_pk_fma_f32 v[12:13], v[20:21], v[12:13], v[16:17] op_sel_hi:[0,1,1]
	v_mov_b32_e32 v16, v25
	v_pk_mul_f32 v[22:23], v[36:37], v[18:19] op_sel_hi:[1,0]
	v_pk_mul_f32 v[18:19], v[38:39], v[18:19] op_sel_hi:[1,0]
	s_waitcnt vmcnt(15)
	v_pk_fma_f32 v[8:9], v[8:9], v[16:17], v[22:23] op_sel_hi:[1,0,1]
	v_pk_fma_f32 v[10:11], v[10:11], v[16:17], v[18:19] op_sel_hi:[1,0,1]
	v_add_co_u32_e32 v16, vcc, s20, v74
	s_nop 1
	v_addc_co_u32_e32 v17, vcc, 0, v75, vcc
	global_store_dwordx4 v[16:17], v[8:11], off nt
	v_mov_b32_e32 v16, v21
	ds_read2_b32 v[18:19], v171 offset0:112 offset1:120
	ds_read2_b32 v[20:21], v161 offset0:240 offset1:248
	v_pk_fma_f32 v[8:9], v[16:17], v[8:9], v[12:13] op_sel_hi:[0,1,1]
	ds_read2_b32 v[12:13], v161 offset0:112 offset1:120
	v_pk_fma_f32 v[10:11], v[16:17], v[10:11], v[14:15] op_sel_hi:[0,1,1]
	s_waitcnt lgkmcnt(2)
	v_pk_mul_f32 v[14:15], v[36:37], v[18:19] op_sel_hi:[1,0]
	s_waitcnt vmcnt(15) lgkmcnt(1)
	v_pk_fma_f32 v[4:5], v[4:5], v[20:21], v[14:15] op_sel_hi:[1,0,1]
	v_pk_mul_f32 v[14:15], v[38:39], v[18:19] op_sel_hi:[1,0]
	s_nop 0
	v_pk_fma_f32 v[6:7], v[6:7], v[20:21], v[14:15] op_sel_hi:[1,0,1]
	v_add_co_u32_e32 v14, vcc, s20, v72
	s_nop 1
	v_addc_co_u32_e32 v15, vcc, 0, v73, vcc
	global_store_dwordx4 v[14:15], v[4:7], off nt
	s_waitcnt lgkmcnt(0)
	s_nop 0
	v_pk_fma_f32 v[6:7], v[12:13], v[6:7], v[10:11] op_sel_hi:[0,1,1]
	v_mov_b32_e32 v10, v19
	v_pk_fma_f32 v[4:5], v[12:13], v[4:5], v[8:9] op_sel_hi:[0,1,1]
	v_mov_b32_e32 v8, v21
	v_pk_mul_f32 v[14:15], v[36:37], v[10:11] op_sel_hi:[1,0]
	v_pk_mul_f32 v[10:11], v[38:39], v[10:11] op_sel_hi:[1,0]
	s_waitcnt vmcnt(15)
	v_pk_fma_f32 v[0:1], v[0:1], v[8:9], v[14:15] op_sel_hi:[1,0,1]
	v_pk_fma_f32 v[2:3], v[2:3], v[8:9], v[10:11] op_sel_hi:[1,0,1]
	v_add_co_u32_e32 v8, vcc, s20, v70
	s_nop 1
	v_addc_co_u32_e32 v9, vcc, 0, v71, vcc
	global_store_dwordx4 v[8:9], v[0:3], off nt
	v_mov_b32_e32 v8, v13
	s_nop 0
	v_pk_fma_f32 v[0:1], v[8:9], v[0:1], v[4:5] op_sel_hi:[0,1,1]
	v_pk_fma_f32 v[2:3], v[8:9], v[2:3], v[6:7] op_sel_hi:[0,1,1]
	ds_write_b128 v133, v[0:3] offset:2048
	v_mov_b32_e32 v0, 0
	s_waitcnt lgkmcnt(0)
	s_barrier
	s_and_saveexec_b64 s[10:11], s[2:3]
	s_cbranch_execz .LBB0_330
	ds_read2st64_b32 v[0:1], v83 offset0:8 offset1:10
	ds_read2st64_b32 v[2:3], v83 offset0:12 offset1:14
	ds_read2st64_b32 v[4:5], v83 offset0:16 offset1:18
	ds_read2st64_b32 v[6:7], v83 offset0:20 offset1:22
	v_and_b32_e32 v8, 64, v81
	s_waitcnt lgkmcnt(3)
	v_add_f32_e32 v0, 0, v0
	v_add_f32_e32 v0, v0, v1
	s_waitcnt lgkmcnt(2)
	v_add_f32_e32 v0, v0, v2
	v_add_f32_e32 v0, v0, v3
	s_waitcnt lgkmcnt(1)
	v_add_f32_e32 v0, v0, v4
	v_add_f32_e32 v0, v0, v5
	v_add_u32_e32 v2, 64, v8
	v_xor_b32_e32 v3, 32, v81
	s_waitcnt lgkmcnt(0)
	v_add_f32_e32 v0, v0, v6
	v_cmp_lt_i32_e32 vcc, v3, v2
	v_add_f32_e32 v0, v0, v7
	v_mul_f32_e32 v1, v0, v0
	v_cndmask_b32_e32 v3, v81, v3, vcc
	v_lshlrev_b32_e32 v3, 2, v3
	ds_bpermute_b32 v1, v3, v1
	v_xor_b32_e32 v3, 16, v81
	v_cmp_lt_i32_e32 vcc, v3, v2
	s_waitcnt lgkmcnt(0)
	v_fmac_f32_e32 v1, v0, v0
	v_cndmask_b32_e32 v3, v81, v3, vcc
	v_lshlrev_b32_e32 v3, 2, v3
	ds_bpermute_b32 v3, v3, v1
	s_waitcnt lgkmcnt(0)
	v_add_f32_e32 v1, v1, v3
	v_xor_b32_e32 v3, 8, v81
	v_cmp_lt_i32_e32 vcc, v3, v2
	s_nop 1
	v_cndmask_b32_e32 v3, v81, v3, vcc
	v_lshlrev_b32_e32 v3, 2, v3
	ds_bpermute_b32 v3, v3, v1
	s_waitcnt lgkmcnt(0)
	v_add_f32_e32 v1, v1, v3
	v_xor_b32_e32 v3, 4, v81
	v_cmp_lt_i32_e32 vcc, v3, v2
	s_nop 1
	v_cndmask_b32_e32 v3, v81, v3, vcc
	v_lshlrev_b32_e32 v3, 2, v3
	ds_bpermute_b32 v3, v3, v1
	s_waitcnt lgkmcnt(0)
	v_add_f32_e32 v1, v1, v3
	v_xor_b32_e32 v3, 2, v81
	v_cmp_lt_i32_e32 vcc, v3, v2
	s_nop 1
	v_cndmask_b32_e32 v3, v81, v3, vcc
	v_lshlrev_b32_e32 v3, 2, v3
	ds_bpermute_b32 v3, v3, v1
	s_waitcnt lgkmcnt(0)
	v_add_f32_e32 v1, v1, v3
	v_xor_b32_e32 v3, 1, v81
	v_cmp_lt_i32_e32 vcc, v3, v2
	s_nop 1
	v_cndmask_b32_e32 v2, v81, v3, vcc
	v_lshlrev_b32_e32 v2, 2, v2
	ds_bpermute_b32 v2, v2, v1
	v_and_b32_e32 v3, 63, v82
	v_cmp_eq_u32_e32 vcc, 0, v3
	s_and_saveexec_b64 s[12:13], vcc
	s_cbranch_execz .LBB0_329
	v_ashrrev_i32_e32 v3, 4, v68
	v_add_u32_e32 v3, s91, v3
	s_waitcnt lgkmcnt(0)
	v_add_f32_e32 v1, v1, v2
	ds_write_b32 v3, v1 offset:6144

.LBB0_2056:
	v_mov_b32_e32 v96, v101
	ds_read_b128 v[0:3], v135
	ds_read_b128 v[4:7], v135 offset:32
	s_load_dwordx2 s[0:1], s[40:41], 0x80
	s_add_i32 s39, s45, s38
	s_waitcnt lgkmcnt(0)
	v_mfma_f32_32x32x16_bf16 v[64:79], v[0:3], v[80:83], 0
	ds_read_b128 v[0:3], v135 offset:64
	s_add_u32 s0, s0, s36
	s_addc_u32 s1, s1, s37
	s_add_i32 s38, s38, 1
	s_nop 0
	v_mfma_f32_32x32x16_bf16 v[64:79], v[4:7], v[84:87], v[64:79]
	s_waitcnt lgkmcnt(0)
	v_mfma_f32_32x32x16_bf16 v[64:79], v[0:3], v[88:91], v[64:79]
	ds_read_b128 v[0:3], v135 offset:96
	s_waitcnt lgkmcnt(0)
	v_mfma_f32_32x32x16_bf16 v[64:79], v[0:3], v[92:95], v[64:79]
	ds_read_b128 v[0:3], v135 offset:4608
	s_waitcnt lgkmcnt(0)
	v_mfma_f32_32x32x16_bf16 v[48:63], v[0:3], v[80:83], 0
	ds_read_b128 v[0:3], v135 offset:4640
	s_waitcnt lgkmcnt(0)
	v_mfma_f32_32x32x16_bf16 v[48:63], v[0:3], v[84:87], v[48:63]
	ds_read_b128 v[0:3], v135 offset:4672
	s_waitcnt lgkmcnt(0)
	v_mfma_f32_32x32x16_bf16 v[48:63], v[0:3], v[88:91], v[48:63]
	ds_read_b128 v[0:3], v135 offset:4704
	s_waitcnt lgkmcnt(0)
	v_mfma_f32_32x32x16_bf16 v[48:63], v[0:3], v[92:95], v[48:63]
	ds_read_b128 v[0:3], v135 offset:9216
	s_waitcnt lgkmcnt(0)
	v_mfma_f32_32x32x16_bf16 v[32:47], v[0:3], v[80:83], 0
	ds_read_b128 v[0:3], v135 offset:9248
	s_waitcnt lgkmcnt(0)
	v_mfma_f32_32x32x16_bf16 v[32:47], v[0:3], v[84:87], v[32:47]
	ds_read_b128 v[0:3], v135 offset:9280
	s_waitcnt lgkmcnt(0)
	v_mfma_f32_32x32x16_bf16 v[32:47], v[0:3], v[88:91], v[32:47]
	ds_read_b128 v[0:3], v135 offset:9312
	s_waitcnt lgkmcnt(0)
	v_mfma_f32_32x32x16_bf16 v[32:47], v[0:3], v[92:95], v[32:47]
	ds_read_b128 v[0:3], v135 offset:13824
	s_waitcnt lgkmcnt(0)
	v_mfma_f32_32x32x16_bf16 v[16:31], v[0:3], v[80:83], 0
	ds_read_b128 v[0:3], v135 offset:13856
	s_waitcnt lgkmcnt(0)
	v_mfma_f32_32x32x16_bf16 v[16:31], v[0:3], v[84:87], v[16:31]
	ds_read_b128 v[0:3], v135 offset:13888
	s_waitcnt lgkmcnt(0)
	v_mfma_f32_32x32x16_bf16 v[16:31], v[0:3], v[88:91], v[16:31]
	ds_read_b128 v[0:3], v135 offset:13920
	s_waitcnt lgkmcnt(0)
	v_mfma_f32_32x32x16_bf16 v[16:31], v[0:3], v[92:95], v[16:31]
	ds_read_b128 v[0:3], v135 offset:18432
	s_waitcnt lgkmcnt(0)
	v_mfma_f32_32x32x16_bf16 v[0:15], v[0:3], v[80:83], 0
	ds_read_b128 v[80:83], v135 offset:18464
	s_waitcnt lgkmcnt(0)
	v_mfma_f32_32x32x16_bf16 v[0:15], v[80:83], v[84:87], v[0:15]
	ds_read_b128 v[80:83], v135 offset:18496
	s_waitcnt lgkmcnt(0)
	v_mfma_f32_32x32x16_bf16 v[0:15], v[80:83], v[88:91], v[0:15]
	ds_read_b128 v[80:83], v135 offset:18528
	s_waitcnt lgkmcnt(0)
	v_mfma_f32_32x32x16_bf16 v[0:15], v[80:83], v[92:95], v[0:15]
	global_load_dword v80, v97, s[0:1]
	v_add_u32_e32 v94, 0x80, v96
	v_cmp_le_i32_e64 s[0:1], v100, v96
	v_cmp_gt_i32_e32 vcc, v100, v94
	s_or_b64 s[0:1], s[0:1], vcc
	v_readlane_b32 vcc_lo, v254, 37
	v_readlane_b32 vcc_hi, v254, 38
	s_or_b64 vcc, s[0:1], vcc
	v_cmp_ge_i32_e64 s[0:1], v100, v94
	v_cndmask_b32_e32 v64, v64, v200, vcc
	v_cmp_lt_i32_e32 vcc, v100, v96
	s_or_b64 s[0:1], vcc, s[0:1]
	v_readlane_b32 vcc_lo, v254, 39
	v_readlane_b32 vcc_hi, v254, 40
	s_or_b64 vcc, s[0:1], vcc
	v_cmp_gt_i32_e64 s[0:1], v104, v94
	v_cndmask_b32_e32 v65, v65, v200, vcc
	v_cmp_le_i32_e32 vcc, v104, v96
	s_or_b64 s[0:1], vcc, s[0:1]
	v_readlane_b32 vcc_lo, v254, 20
	v_readlane_b32 vcc_hi, v254, 21
	s_or_b64 vcc, s[0:1], vcc
	v_cmp_gt_i32_e64 s[0:1], v105, v94
	v_cndmask_b32_e32 v66, v66, v200, vcc
	v_cmp_le_i32_e32 vcc, v105, v96
	s_or_b64 s[0:1], vcc, s[0:1]
	v_readlane_b32 vcc_lo, v254, 18
	v_readlane_b32 vcc_hi, v254, 19
	s_or_b64 vcc, s[0:1], vcc
	v_cmp_gt_i32_e64 s[0:1], v106, v94
	v_cndmask_b32_e32 v67, v67, v200, vcc
	v_cmp_le_i32_e32 vcc, v106, v96
	s_or_b64 s[0:1], vcc, s[0:1]
	v_readlane_b32 vcc_lo, v254, 41
	v_readlane_b32 vcc_hi, v254, 42
	s_or_b64 vcc, s[0:1], vcc
	v_cmp_gt_i32_e64 s[0:1], v107, v94
	v_cndmask_b32_e32 v68, v68, v200, vcc
	v_cmp_le_i32_e32 vcc, v107, v96
	s_or_b64 s[0:1], vcc, s[0:1]
	v_readlane_b32 vcc_lo, v254, 22
	v_readlane_b32 vcc_hi, v254, 23
	s_or_b64 vcc, s[0:1], vcc
	v_cmp_gt_i32_e64 s[0:1], v108, v94
	v_cndmask_b32_e32 v69, v69, v200, vcc
	v_cmp_le_i32_e32 vcc, v108, v96
	s_or_b64 s[0:1], vcc, s[0:1]
	v_readlane_b32 vcc_lo, v254, 24
	v_readlane_b32 vcc_hi, v254, 25
	s_or_b64 vcc, s[0:1], vcc
	v_cmp_gt_i32_e64 s[0:1], v109, v94
	v_cndmask_b32_e32 v70, v70, v200, vcc
	v_cmp_le_i32_e32 vcc, v109, v96
	s_or_b64 s[0:1], vcc, s[0:1]
	v_readlane_b32 vcc_lo, v254, 26
	v_readlane_b32 vcc_hi, v254, 27
	s_or_b64 vcc, s[0:1], vcc
	v_cmp_gt_i32_e64 s[0:1], v110, v94
	v_cndmask_b32_e32 v71, v71, v200, vcc
	v_cmp_le_i32_e32 vcc, v110, v96
	s_or_b64 s[0:1], vcc, s[0:1]
	v_readlane_b32 vcc_lo, v254, 28
	v_readlane_b32 vcc_hi, v254, 29
	s_or_b64 vcc, s[0:1], vcc
	v_cmp_gt_i32_e64 s[0:1], v111, v94
	v_cndmask_b32_e32 v72, v72, v200, vcc
	v_cmp_le_i32_e32 vcc, v111, v96
	s_or_b64 s[0:1], vcc, s[0:1]
	v_readlane_b32 vcc_lo, v254, 32
	v_readlane_b32 vcc_hi, v254, 33
	s_or_b64 vcc, s[0:1], vcc
	v_cmp_gt_i32_e64 s[0:1], v112, v94
	v_cndmask_b32_e32 v73, v73, v200, vcc
	v_cmp_le_i32_e32 vcc, v112, v96
	s_or_b64 s[0:1], vcc, s[0:1]
	v_readlane_b32 vcc_lo, v254, 34
	v_readlane_b32 vcc_hi, v254, 35
	s_or_b64 vcc, s[0:1], vcc
	v_cmp_gt_i32_e64 s[0:1], v113, v94
	v_cndmask_b32_e32 v74, v74, v200, vcc
	v_cmp_le_i32_e32 vcc, v113, v96
	s_or_b64 s[0:1], vcc, s[0:1]
	v_readlane_b32 vcc_lo, v254, 5
	v_readlane_b32 vcc_hi, v254, 6
	s_or_b64 vcc, s[0:1], vcc
	v_cmp_gt_i32_e64 s[0:1], v114, v94
	v_cndmask_b32_e32 v75, v75, v200, vcc
	v_cmp_le_i32_e32 vcc, v114, v96
	s_or_b64 s[0:1], vcc, s[0:1]
	v_readlane_b32 vcc_lo, v254, 8
	v_readlane_b32 vcc_hi, v254, 9
	s_or_b64 vcc, s[0:1], vcc
	v_cmp_gt_i32_e64 s[0:1], v115, v94
	v_cndmask_b32_e32 v76, v76, v200, vcc
	v_cmp_le_i32_e32 vcc, v115, v96
	s_or_b64 s[0:1], vcc, s[0:1]
	v_readlane_b32 vcc_lo, v254, 30
	v_readlane_b32 vcc_hi, v254, 31
	s_or_b64 vcc, s[0:1], vcc
	v_cmp_gt_i32_e64 s[0:1], v116, v94
	v_cndmask_b32_e32 v77, v77, v200, vcc
	v_cmp_le_i32_e32 vcc, v116, v96
	s_or_b64 s[0:1], vcc, s[0:1]
	v_readlane_b32 vcc_lo, v254, 58
	v_readlane_b32 vcc_hi, v254, 59
	s_or_b64 vcc, s[0:1], vcc
	v_cmp_gt_i32_e64 s[0:1], v117, v94
	v_cndmask_b32_e32 v85, v78, v200, vcc
	v_cmp_le_i32_e32 vcc, v117, v96
	s_or_b64 s[0:1], vcc, s[0:1]
	v_readlane_b32 vcc_lo, v254, 60
	v_readlane_b32 vcc_hi, v254, 61
	s_or_b64 vcc, s[0:1], vcc
	v_readlane_b32 s0, v254, 62
	v_readlane_b32 s1, v254, 63
	s_waitcnt vmcnt(0)
	v_max3_f32 v81, v80, v64, v65
	v_max3_f32 v81, v81, v66, v67
	v_cndmask_b32_e64 v93, v48, v200, s[0:1]
	v_readlane_b32 s0, v255, 0
	v_readlane_b32 s1, v255, 1
	v_max3_f32 v81, v81, v68, v69
	v_max3_f32 v81, v81, v70, v71
	v_cndmask_b32_e64 v90, v49, v200, s[0:1]
	v_readlane_b32 s0, v255, 2
	v_readlane_b32 s1, v255, 3
	v_max3_f32 v81, v81, v72, v73
	v_max3_f32 v81, v81, v74, v75
	v_cndmask_b32_e64 v91, v50, v200, s[0:1]
	v_readlane_b32 s0, v255, 4
	v_readlane_b32 s1, v255, 5
	v_max3_f32 v81, v81, v76, v77
	v_cndmask_b32_e32 v92, v79, v200, vcc
	v_cndmask_b32_e64 v88, v51, v200, s[0:1]
	v_readlane_b32 s0, v255, 6
	v_readlane_b32 s1, v255, 7
	v_max3_f32 v78, v81, v85, v92
	v_max3_f32 v48, v78, v93, v90
	v_cndmask_b32_e64 v89, v52, v200, s[0:1]
	v_readlane_b32 s0, v255, 8
	v_readlane_b32 s1, v255, 9
	v_cmp_le_i32_e32 vcc, v118, v96
	v_max3_f32 v48, v48, v91, v88
	v_cndmask_b32_e64 v86, v53, v200, s[0:1]
	v_readlane_b32 s0, v255, 10
	v_readlane_b32 s1, v255, 11
	v_max3_f32 v48, v48, v89, v86
	v_cndmask_b32_e64 v52, v39, v200, s[6:7]
	v_cndmask_b32_e64 v87, v54, v200, s[0:1]
	v_readlane_b32 s0, v255, 12
	v_readlane_b32 s1, v255, 13
	v_cndmask_b32_e64 v51, v40, v200, s[50:51]
	v_cndmask_b32_e64 v50, v41, v200, s[52:53]
	v_cndmask_b32_e64 v83, v55, v200, s[0:1]
	v_readlane_b32 s0, v255, 14
	v_readlane_b32 s1, v255, 15
	v_max3_f32 v48, v48, v87, v83
	v_cndmask_b32_e64 v49, v42, v200, s[54:55]
	v_cndmask_b32_e64 v84, v56, v200, s[0:1]
	v_readlane_b32 s0, v255, 16
	v_readlane_b32 s1, v255, 17
	v_cndmask_b32_e64 v42, v45, v200, s[60:61]
	v_cndmask_b32_e64 v41, v46, v200, s[62:63]
	v_cndmask_b32_e64 v81, v57, v200, s[0:1]
	v_readlane_b32 s0, v255, 18
	v_readlane_b32 s1, v255, 19
	v_max3_f32 v48, v48, v84, v81
	v_cndmask_b32_e64 v40, v47, v200, s[64:65]
	v_cndmask_b32_e64 v82, v58, v200, s[0:1]
	v_readlane_b32 s0, v255, 20
	v_readlane_b32 s1, v255, 21
	v_cndmask_b32_e64 v39, v16, v200, s[66:67]
	s_nop 0
	v_cndmask_b32_e64 v78, v59, v200, s[0:1]
	v_readlane_b32 s0, v255, 22
	v_readlane_b32 s1, v255, 23
	v_max3_f32 v48, v48, v82, v78
	s_nop 0
	v_cndmask_b32_e64 v79, v60, v200, s[0:1]
	v_readlane_b32 s0, v255, 24
	v_readlane_b32 s1, v255, 25
	s_nop 1
	v_cndmask_b32_e64 v61, v61, v200, s[0:1]
	v_readlane_b32 s0, v255, 26
	v_readlane_b32 s1, v255, 27
	v_max3_f32 v48, v48, v79, v61
	s_nop 0
	v_cndmask_b32_e64 v62, v62, v200, s[0:1]
	v_readlane_b32 s0, v255, 28
	v_readlane_b32 s1, v255, 29
	s_nop 1
	v_cndmask_b32_e64 v59, v63, v200, s[0:1]
	v_readlane_b32 s0, v255, 30
	v_readlane_b32 s1, v255, 31
	v_max3_f32 v48, v48, v62, v59
	s_nop 0
	v_cndmask_b32_e64 v60, v32, v200, s[0:1]
	v_readlane_b32 s0, v255, 32
	v_readlane_b32 s1, v255, 33
	s_nop 1
	v_cndmask_b32_e64 v57, v33, v200, s[0:1]
	v_readlane_b32 s0, v255, 34
	v_readlane_b32 s1, v255, 35
	v_max3_f32 v32, v48, v60, v57
	v_cndmask_b32_e64 v48, v43, v200, s[56:57]
	v_cndmask_b32_e64 v58, v34, v200, s[0:1]
	v_readlane_b32 s0, v255, 36
	v_readlane_b32 s1, v255, 37
	v_cndmask_b32_e64 v43, v44, v200, s[58:59]
	v_cndmask_b32_e64 v34, v21, v200, s[76:77]
	v_cndmask_b32_e64 v55, v35, v200, s[0:1]
	v_readlane_b32 s0, v255, 38
	v_readlane_b32 s1, v255, 39
	v_max3_f32 v32, v32, v58, v55
	v_cndmask_b32_e64 v35, v20, v200, s[74:75]
	v_cndmask_b32_e64 v56, v36, v200, s[0:1]
	v_readlane_b32 s0, v255, 40
	v_readlane_b32 s1, v255, 41
	v_cndmask_b32_e64 v36, v19, v200, s[72:73]
	v_cndmask_b32_e64 v33, v22, v200, s[78:79]
	v_cndmask_b32_e64 v53, v37, v200, s[0:1]
	v_readlane_b32 s0, v255, 42
	v_readlane_b32 s1, v255, 43
	v_max3_f32 v32, v32, v56, v53
	v_cndmask_b32_e64 v37, v18, v200, s[70:71]
	v_cndmask_b32_e64 v54, v38, v200, s[0:1]
	v_cmp_gt_i32_e64 s[0:1], v100, v96
	s_or_b64 s[0:1], vcc, s[0:1]
	s_or_b64 vcc, s[0:1], s[42:43]
	v_cndmask_b32_e32 v0, v0, v200, vcc
	v_cmp_le_i32_e32 vcc, v119, v96
	v_cmp_gt_i32_e64 s[0:1], v119, v94
	s_or_b64 s[0:1], vcc, s[0:1]
	s_or_b64 vcc, s[0:1], s[4:5]
	v_cndmask_b32_e32 v1, v1, v200, vcc
	v_cmp_le_i32_e32 vcc, v120, v96
	v_cmp_gt_i32_e64 s[0:1], v120, v94
	s_or_b64 s[0:1], vcc, s[0:1]
	s_or_b64 vcc, s[0:1], s[48:49]
	v_cndmask_b32_e32 v2, v2, v200, vcc
	v_cmp_le_i32_e32 vcc, v121, v96
	v_cmp_gt_i32_e64 s[0:1], v121, v94
	s_or_b64 s[0:1], vcc, s[0:1]
	s_or_b64 vcc, s[0:1], s[8:9]
	v_cndmask_b32_e32 v3, v3, v200, vcc
	v_cmp_le_i32_e32 vcc, v122, v96
	v_cmp_gt_i32_e64 s[0:1], v122, v94
	s_or_b64 s[0:1], vcc, s[0:1]
	s_or_b64 vcc, s[0:1], s[10:11]
	v_cndmask_b32_e32 v4, v4, v200, vcc
	v_cmp_le_i32_e32 vcc, v123, v96
	v_cmp_gt_i32_e64 s[0:1], v123, v94
	s_or_b64 s[0:1], vcc, s[0:1]
	s_or_b64 vcc, s[0:1], s[12:13]
	v_cndmask_b32_e32 v5, v5, v200, vcc
	v_cmp_le_i32_e32 vcc, v124, v96
	v_cmp_gt_i32_e64 s[0:1], v124, v94
	s_or_b64 s[0:1], vcc, s[0:1]
	s_or_b64 vcc, s[0:1], s[14:15]
	v_cndmask_b32_e32 v6, v6, v200, vcc
	v_cmp_le_i32_e32 vcc, v125, v96
	v_cmp_gt_i32_e64 s[0:1], v125, v94
	s_or_b64 s[0:1], vcc, s[0:1]
	s_or_b64 vcc, s[0:1], s[16:17]
	v_cndmask_b32_e32 v7, v7, v200, vcc
	v_cmp_le_i32_e32 vcc, v126, v96
	v_cmp_gt_i32_e64 s[0:1], v126, v94
	s_or_b64 s[0:1], vcc, s[0:1]
	s_or_b64 vcc, s[0:1], s[18:19]
	v_cndmask_b32_e32 v8, v8, v200, vcc
	v_cmp_le_i32_e32 vcc, v127, v96
	v_cmp_gt_i32_e64 s[0:1], v127, v94
	s_or_b64 s[0:1], vcc, s[0:1]
	s_or_b64 vcc, s[0:1], s[20:21]
	v_max3_f32 v32, v32, v54, v52
	v_cndmask_b32_e32 v9, v9, v200, vcc
	v_cmp_le_i32_e32 vcc, v128, v96
	v_cmp_gt_i32_e64 s[0:1], v128, v94
	v_max3_f32 v32, v32, v51, v50
	s_or_b64 s[0:1], vcc, s[0:1]
	v_max3_f32 v32, v32, v49, v48
	s_or_b64 vcc, s[0:1], s[22:23]
	v_max3_f32 v32, v32, v43, v42
	v_cndmask_b32_e32 v10, v10, v200, vcc
	v_cmp_le_i32_e32 vcc, v129, v96
	v_cmp_gt_i32_e64 s[0:1], v129, v94
	v_max3_f32 v32, v32, v41, v40
	v_cndmask_b32_e64 v38, v17, v200, s[68:69]
	s_or_b64 s[0:1], vcc, s[0:1]
	v_max3_f32 v16, v32, v39, v38
	s_or_b64 vcc, s[0:1], s[24:25]
	v_max3_f32 v16, v16, v37, v36
	v_cndmask_b32_e32 v11, v11, v200, vcc
	v_cmp_le_i32_e32 vcc, v130, v96
	v_cmp_gt_i32_e64 s[0:1], v130, v94
	v_max3_f32 v16, v16, v35, v34
	v_cndmask_b32_e64 v32, v23, v200, s[80:81]
	s_or_b64 s[0:1], vcc, s[0:1]
	v_max3_f32 v16, v16, v33, v32
	v_cndmask_b32_e64 v23, v24, v200, s[82:83]
	v_cndmask_b32_e64 v22, v25, v200, s[84:85]
	s_or_b64 vcc, s[0:1], s[26:27]
	v_max3_f32 v16, v16, v23, v22
	v_cndmask_b32_e64 v21, v26, v200, s[86:87]
	v_cndmask_b32_e64 v20, v27, v200, s[88:89]
	v_cndmask_b32_e32 v12, v12, v200, vcc
	v_cmp_le_i32_e32 vcc, v131, v96
	v_cmp_gt_i32_e64 s[0:1], v131, v94
	v_max3_f32 v16, v16, v21, v20
	v_cndmask_b32_e64 v19, v28, v200, s[90:91]
	v_cndmask_b32_e64 v18, v29, v200, s[92:93]
	s_or_b64 s[0:1], vcc, s[0:1]
	v_max3_f32 v24, v16, v19, v18
	v_cndmask_b32_e64 v17, v30, v200, s[94:95]
	v_cndmask_b32_e64 v16, v31, v200, s[96:97]
	s_or_b64 vcc, s[0:1], s[28:29]
	v_max3_f32 v24, v24, v17, v16
	v_cndmask_b32_e32 v13, v13, v200, vcc
	v_cmp_le_i32_e32 vcc, v132, v96
	v_cmp_gt_i32_e64 s[0:1], v132, v94
	v_max3_f32 v24, v24, v0, v1
	s_or_b64 s[0:1], vcc, s[0:1]
	v_max3_f32 v24, v24, v2, v3
	s_or_b64 vcc, s[0:1], s[30:31]
	v_max3_f32 v24, v24, v4, v5
	v_cndmask_b32_e32 v14, v14, v200, vcc
	v_cmp_le_i32_e32 vcc, v133, v96
	v_cmp_gt_i32_e64 s[0:1], v133, v94
	v_max3_f32 v24, v24, v6, v7
	s_or_b64 s[0:1], vcc, s[0:1]
	v_and_b32_e32 v26, 64, v198
	v_max3_f32 v24, v24, v8, v9
	s_or_b64 vcc, s[0:1], s[34:35]
	v_xor_b32_e32 v25, 32, v198
	v_add_u32_e32 v26, 64, v26
	v_max3_f32 v24, v24, v10, v11
	v_cndmask_b32_e32 v15, v15, v200, vcc
	v_cmp_lt_i32_e32 vcc, v25, v26
	v_max3_f32 v24, v24, v12, v13
	v_max3_f32 v24, v24, v14, v15
	v_cndmask_b32_e32 v25, v198, v25, vcc
	v_lshlrev_b32_e32 v25, 2, v25
	ds_bpermute_b32 v26, v25, v24
	s_lshr_b32 s1, s39, 2
	s_mulk_i32 s1, 0x4080
	s_add_i32 s2, s1, 0x20400
	s_add_i32 s0, s44, s33
	s_waitcnt lgkmcnt(0)
	v_max_f32_e32 v26, v26, v26
	v_max_f32_e32 v24, v24, v26
	v_sub_f32_e32 v26, v64, v24
	v_mul_f32_e32 v26, 0x3fb8aa3b, v26
	v_sub_f32_e32 v28, v65, v24
	v_exp_f32_e32 v26, v26
	v_mul_f32_e32 v28, 0x3fb8aa3b, v28
	v_sub_f32_e32 v29, v66, v24
	v_exp_f32_e32 v28, v28
	v_mul_f32_e32 v29, 0x3fb8aa3b, v29
	v_sub_f32_e32 v30, v67, v24
	v_exp_f32_e32 v29, v29
	v_mul_f32_e32 v30, 0x3fb8aa3b, v30
	v_sub_f32_e32 v31, v68, v24
	v_exp_f32_e32 v30, v30
	v_mul_f32_e32 v31, 0x3fb8aa3b, v31
	v_sub_f32_e32 v44, v69, v24
	v_add_f32_e32 v27, 0, v26
	v_exp_f32_e32 v31, v31
	v_mul_f32_e32 v44, 0x3fb8aa3b, v44
	v_sub_f32_e32 v45, v70, v24
	v_add_f32_e32 v27, v28, v27
	v_exp_f32_e32 v44, v44
	v_mul_f32_e32 v45, 0x3fb8aa3b, v45
	v_sub_f32_e32 v46, v71, v24
	v_add_f32_e32 v27, v29, v27
	v_exp_f32_e32 v45, v45
	v_mul_f32_e32 v46, 0x3fb8aa3b, v46
	v_sub_f32_e32 v47, v72, v24
	v_add_f32_e32 v27, v30, v27
	v_exp_f32_e32 v46, v46
	v_mul_f32_e32 v47, 0x3fb8aa3b, v47
	v_sub_f32_e32 v63, v73, v24
	v_add_f32_e32 v27, v31, v27
	v_exp_f32_e32 v47, v47
	v_mul_f32_e32 v63, 0x3fb8aa3b, v63
	v_sub_f32_e32 v64, v74, v24
	v_add_f32_e32 v27, v44, v27
	v_exp_f32_e32 v63, v63
	v_mul_f32_e32 v64, 0x3fb8aa3b, v64
	v_sub_f32_e32 v65, v75, v24
	v_add_f32_e32 v27, v45, v27
	v_exp_f32_e32 v64, v64
	v_mul_f32_e32 v65, 0x3fb8aa3b, v65
	v_sub_f32_e32 v66, v76, v24
	v_add_f32_e32 v27, v46, v27
	v_exp_f32_e32 v65, v65
	v_mul_f32_e32 v66, 0x3fb8aa3b, v66
	v_sub_f32_e32 v67, v77, v24
	v_add_f32_e32 v27, v47, v27
	v_exp_f32_e32 v66, v66
	v_mul_f32_e32 v67, 0x3fb8aa3b, v67
	v_sub_f32_e32 v68, v85, v24
	v_add_f32_e32 v27, v63, v27
	v_exp_f32_e32 v67, v67
	v_mul_f32_e32 v68, 0x3fb8aa3b, v68
	v_sub_f32_e32 v69, v92, v24
	v_add_f32_e32 v27, v64, v27
	v_exp_f32_e32 v68, v68
	v_mul_f32_e32 v69, 0x3fb8aa3b, v69
	v_sub_f32_e32 v70, v93, v24
	v_add_f32_e32 v27, v65, v27
	v_exp_f32_e32 v69, v69
	v_mul_f32_e32 v70, 0x3fb8aa3b, v70
	v_sub_f32_e32 v71, v90, v24
	v_add_f32_e32 v27, v66, v27
	v_exp_f32_e32 v70, v70
	v_mul_f32_e32 v71, 0x3fb8aa3b, v71
	v_sub_f32_e32 v72, v91, v24
	v_add_f32_e32 v27, v67, v27
	v_exp_f32_e32 v71, v71
	v_mul_f32_e32 v72, 0x3fb8aa3b, v72
	v_sub_f32_e32 v73, v88, v24
	v_add_f32_e32 v27, v68, v27
	v_exp_f32_e32 v72, v72
	v_mul_f32_e32 v73, 0x3fb8aa3b, v73
	v_sub_f32_e32 v74, v89, v24
	v_add_f32_e32 v27, v69, v27
	v_exp_f32_e32 v73, v73
	v_mul_f32_e32 v74, 0x3fb8aa3b, v74
	v_sub_f32_e32 v75, v86, v24
	v_add_f32_e32 v27, v70, v27
	v_exp_f32_e32 v74, v74
	v_mul_f32_e32 v75, 0x3fb8aa3b, v75
	v_sub_f32_e32 v76, v87, v24
	v_add_f32_e32 v27, v71, v27
	v_exp_f32_e32 v75, v75
	v_mul_f32_e32 v76, 0x3fb8aa3b, v76
	v_sub_f32_e32 v77, v83, v24
	v_add_f32_e32 v27, v72, v27
	v_exp_f32_e32 v76, v76
	v_mul_f32_e32 v77, 0x3fb8aa3b, v77
	v_sub_f32_e32 v83, v84, v24
	v_add_f32_e32 v27, v73, v27
	v_exp_f32_e32 v77, v77
	v_mul_f32_e32 v83, 0x3fb8aa3b, v83
	v_sub_f32_e32 v81, v81, v24
	v_add_f32_e32 v27, v74, v27
	v_exp_f32_e32 v83, v83
	v_mul_f32_e32 v81, 0x3fb8aa3b, v81
	v_sub_f32_e32 v82, v82, v24
	v_add_f32_e32 v27, v75, v27
	v_exp_f32_e32 v81, v81
	v_mul_f32_e32 v82, 0x3fb8aa3b, v82
	v_sub_f32_e32 v78, v78, v24
	v_add_f32_e32 v27, v76, v27
	v_exp_f32_e32 v82, v82
	v_mul_f32_e32 v78, 0x3fb8aa3b, v78
	v_sub_f32_e32 v79, v79, v24
	v_add_f32_e32 v27, v77, v27
	v_exp_f32_e32 v78, v78
	v_mul_f32_e32 v79, 0x3fb8aa3b, v79
	v_sub_f32_e32 v61, v61, v24
	v_add_f32_e32 v27, v83, v27
	v_exp_f32_e32 v79, v79
	v_mul_f32_e32 v61, 0x3fb8aa3b, v61
	v_sub_f32_e32 v62, v62, v24
	v_add_f32_e32 v27, v81, v27
	v_exp_f32_e32 v61, v61
	v_mul_f32_e32 v62, 0x3fb8aa3b, v62
	v_sub_f32_e32 v59, v59, v24
	v_add_f32_e32 v27, v82, v27
	v_exp_f32_e32 v62, v62
	v_mul_f32_e32 v59, 0x3fb8aa3b, v59
	v_sub_f32_e32 v60, v60, v24
	v_add_f32_e32 v27, v78, v27
	v_exp_f32_e32 v59, v59
	v_mul_f32_e32 v60, 0x3fb8aa3b, v60
	v_sub_f32_e32 v57, v57, v24
	v_add_f32_e32 v27, v79, v27
	v_exp_f32_e32 v60, v60
	v_mul_f32_e32 v57, 0x3fb8aa3b, v57
	v_sub_f32_e32 v58, v58, v24
	v_add_f32_e32 v27, v61, v27
	v_exp_f32_e32 v57, v57
	v_mul_f32_e32 v58, 0x3fb8aa3b, v58
	v_sub_f32_e32 v55, v55, v24
	v_add_f32_e32 v27, v62, v27
	v_exp_f32_e32 v58, v58
	v_mul_f32_e32 v55, 0x3fb8aa3b, v55
	v_sub_f32_e32 v56, v56, v24
	v_add_f32_e32 v27, v59, v27
	v_exp_f32_e32 v55, v55
	v_mul_f32_e32 v56, 0x3fb8aa3b, v56
	v_sub_f32_e32 v53, v53, v24
	v_add_f32_e32 v27, v60, v27
	v_exp_f32_e32 v56, v56
	v_mul_f32_e32 v53, 0x3fb8aa3b, v53
	v_sub_f32_e32 v54, v54, v24
	v_add_f32_e32 v27, v57, v27
	v_exp_f32_e32 v53, v53
	v_mul_f32_e32 v54, 0x3fb8aa3b, v54
	v_sub_f32_e32 v52, v52, v24
	v_add_f32_e32 v27, v58, v27
	v_exp_f32_e32 v54, v54
	v_mul_f32_e32 v52, 0x3fb8aa3b, v52
	v_sub_f32_e32 v51, v51, v24
	v_add_f32_e32 v27, v55, v27
	v_exp_f32_e32 v52, v52
	v_mul_f32_e32 v51, 0x3fb8aa3b, v51
	v_sub_f32_e32 v50, v50, v24
	v_add_f32_e32 v27, v56, v27
	v_exp_f32_e32 v51, v51
	v_mul_f32_e32 v50, 0x3fb8aa3b, v50
	v_sub_f32_e32 v49, v49, v24
	v_add_f32_e32 v27, v53, v27
	v_exp_f32_e32 v50, v50
	v_mul_f32_e32 v49, 0x3fb8aa3b, v49
	v_sub_f32_e32 v48, v48, v24
	v_add_f32_e32 v27, v54, v27
	v_exp_f32_e32 v49, v49
	v_mul_f32_e32 v48, 0x3fb8aa3b, v48
	v_sub_f32_e32 v43, v43, v24
	v_add_f32_e32 v27, v52, v27
	v_exp_f32_e32 v48, v48
	v_mul_f32_e32 v43, 0x3fb8aa3b, v43
	v_sub_f32_e32 v42, v42, v24
	v_add_f32_e32 v27, v51, v27
	v_exp_f32_e32 v84, v43
	v_mul_f32_e32 v42, 0x3fb8aa3b, v42
	v_sub_f32_e32 v41, v41, v24
	v_add_f32_e32 v27, v50, v27
	v_exp_f32_e32 v85, v42
	v_mul_f32_e32 v41, 0x3fb8aa3b, v41
	v_sub_f32_e32 v40, v40, v24
	v_add_f32_e32 v27, v49, v27
	v_exp_f32_e32 v86, v41
	v_mul_f32_e32 v40, 0x3fb8aa3b, v40
	v_sub_f32_e32 v39, v39, v24
	v_add_f32_e32 v27, v48, v27
	v_exp_f32_e32 v87, v40
	v_mul_f32_e32 v39, 0x3fb8aa3b, v39
	v_sub_f32_e32 v38, v38, v24
	v_add_f32_e32 v27, v84, v27
	v_exp_f32_e32 v88, v39
	v_mul_f32_e32 v38, 0x3fb8aa3b, v38
	v_sub_f32_e32 v37, v37, v24
	v_add_f32_e32 v27, v85, v27
	v_exp_f32_e32 v89, v38
	v_mul_f32_e32 v37, 0x3fb8aa3b, v37
	v_sub_f32_e32 v36, v36, v24
	v_sub_f32_e32 v1, v1, v24
	v_add_f32_e32 v27, v86, v27
	v_exp_f32_e32 v90, v37
	v_mul_f32_e32 v36, 0x3fb8aa3b, v36
	v_sub_f32_e32 v35, v35, v24
	v_mul_f32_e32 v1, 0x3fb8aa3b, v1
	v_add_f32_e32 v27, v87, v27
	v_exp_f32_e32 v91, v36
	v_mul_f32_e32 v35, 0x3fb8aa3b, v35
	v_sub_f32_e32 v34, v34, v24
	v_exp_f32_e32 v142, v1
	v_sub_f32_e32 v1, v2, v24
	v_add_f32_e32 v27, v88, v27
	v_exp_f32_e32 v35, v35
	v_mul_f32_e32 v34, 0x3fb8aa3b, v34
	v_sub_f32_e32 v33, v33, v24
	v_mul_f32_e32 v1, 0x3fb8aa3b, v1
	v_add_f32_e32 v27, v89, v27
	v_exp_f32_e32 v92, v34
	v_mul_f32_e32 v33, 0x3fb8aa3b, v33
	v_sub_f32_e32 v32, v32, v24
	v_exp_f32_e32 v143, v1
	v_sub_f32_e32 v1, v3, v24
	v_add_f32_e32 v27, v90, v27
	v_exp_f32_e32 v33, v33
	v_mul_f32_e32 v32, 0x3fb8aa3b, v32
	v_sub_f32_e32 v23, v23, v24
	v_mul_f32_e32 v1, 0x3fb8aa3b, v1
	v_add_f32_e32 v27, v91, v27
	v_exp_f32_e32 v32, v32
	v_mul_f32_e32 v23, 0x3fb8aa3b, v23
	v_sub_f32_e32 v22, v22, v24
	v_exp_f32_e32 v144, v1
	v_sub_f32_e32 v1, v4, v24
	v_add_f32_e32 v27, v35, v27
	v_exp_f32_e32 v93, v23
	v_mul_f32_e32 v22, 0x3fb8aa3b, v22
	v_sub_f32_e32 v21, v21, v24
	v_mul_f32_e32 v1, 0x3fb8aa3b, v1
	v_add_f32_e32 v27, v92, v27
	v_exp_f32_e32 v94, v22
	v_mul_f32_e32 v21, 0x3fb8aa3b, v21
	v_sub_f32_e32 v20, v20, v24
	v_exp_f32_e32 v145, v1
	v_sub_f32_e32 v1, v5, v24
	v_add_f32_e32 v27, v33, v27
	v_exp_f32_e32 v95, v21
	v_mul_f32_e32 v20, 0x3fb8aa3b, v20
	v_sub_f32_e32 v19, v19, v24
	v_mul_f32_e32 v1, 0x3fb8aa3b, v1
	v_add_f32_e32 v27, v32, v27
	v_exp_f32_e32 v96, v20
	v_mul_f32_e32 v19, 0x3fb8aa3b, v19
	v_sub_f32_e32 v18, v18, v24
	v_exp_f32_e32 v146, v1
	v_sub_f32_e32 v1, v6, v24
	v_add_f32_e32 v23, v93, v27
	v_exp_f32_e32 v137, v19
	v_mul_f32_e32 v18, 0x3fb8aa3b, v18
	v_sub_f32_e32 v17, v17, v24
	v_mul_f32_e32 v1, 0x3fb8aa3b, v1
	v_add_f32_e32 v22, v94, v23
	v_exp_f32_e32 v138, v18
	v_mul_f32_e32 v17, 0x3fb8aa3b, v17
	v_sub_f32_e32 v16, v16, v24
	v_exp_f32_e32 v147, v1
	v_sub_f32_e32 v1, v7, v24
	v_add_f32_e32 v21, v95, v22
	v_exp_f32_e32 v139, v17
	v_mul_f32_e32 v16, 0x3fb8aa3b, v16
	v_sub_f32_e32 v0, v0, v24
	v_mul_f32_e32 v1, 0x3fb8aa3b, v1
	v_add_f32_e32 v20, v96, v21
	v_exp_f32_e32 v140, v16
	v_mul_f32_e32 v0, 0x3fb8aa3b, v0
	v_exp_f32_e32 v148, v1
	v_sub_f32_e32 v1, v8, v24
	v_add_f32_e32 v19, v137, v20
	v_exp_f32_e32 v141, v0
	v_mul_f32_e32 v1, 0x3fb8aa3b, v1
	v_add_f32_e32 v18, v138, v19
	v_exp_f32_e32 v149, v1
	v_sub_f32_e32 v1, v9, v24
	v_add_f32_e32 v17, v139, v18
	v_mul_f32_e32 v1, 0x3fb8aa3b, v1
	v_add_f32_e32 v16, v140, v17
	v_exp_f32_e32 v150, v1
	v_sub_f32_e32 v1, v10, v24
	v_add_f32_e32 v0, v141, v16
	v_mul_f32_e32 v1, 0x3fb8aa3b, v1
	v_add_f32_e32 v0, v142, v0
	v_exp_f32_e32 v151, v1
	v_sub_f32_e32 v1, v11, v24
	v_add_f32_e32 v0, v143, v0
	v_mul_f32_e32 v1, 0x3fb8aa3b, v1
	v_add_f32_e32 v0, v144, v0
	v_exp_f32_e32 v152, v1
	v_sub_f32_e32 v1, v12, v24
	v_add_f32_e32 v0, v145, v0
	v_mul_f32_e32 v1, 0x3fb8aa3b, v1
	v_add_f32_e32 v0, v146, v0
	v_exp_f32_e32 v153, v1
	v_sub_f32_e32 v1, v13, v24
	v_add_f32_e32 v0, v147, v0
	v_mul_f32_e32 v1, 0x3fb8aa3b, v1
	v_add_f32_e32 v0, v148, v0
	v_exp_f32_e32 v154, v1
	v_sub_f32_e32 v1, v14, v24
	v_add_f32_e32 v0, v149, v0
	v_mul_f32_e32 v1, 0x3fb8aa3b, v1
	v_add_f32_e32 v0, v150, v0
	v_exp_f32_e32 v155, v1
	v_sub_f32_e32 v1, v15, v24
	v_add_f32_e32 v0, v151, v0
	v_mul_f32_e32 v1, 0x3fb8aa3b, v1
	v_add_f32_e32 v0, v152, v0
	v_exp_f32_e32 v156, v1
	v_add_f32_e32 v0, v153, v0
	v_add_f32_e32 v0, v154, v0
	v_add_f32_e32 v0, v155, v0
	v_add_f32_e32 v0, v156, v0
	ds_bpermute_b32 v1, v25, v0
	v_cvt_pk_bf16_f32 v2, v31, v44
	v_add_u32_e32 v44, 0x9000, v136
	ds_read2_b64 v[4:7], v44 offset1:2
	ds_read2_b64 v[36:39], v44 offset0:4 offset1:6
	v_cvt_pk_bf16_f32 v3, v45, v46
	s_waitcnt lgkmcnt(2)
	v_add_f32_e32 v0, v0, v1
	v_sub_f32_e32 v1, v80, v24
	v_mul_f32_e32 v1, 0x3fb8aa3b, v1
	v_exp_f32_e32 v1, v1
	v_add_u32_e32 v45, 0xd000, v136
	v_cvt_pk_bf16_f32 v40, v47, v63
	v_cvt_pk_bf16_f32 v41, v64, v65
	v_add_f32_e32 v34, v1, v0
	v_cvt_pk_bf16_f32 v0, v26, v28
	v_cvt_pk_bf16_f32 v1, v29, v30
	v_cvt_pk_bf16_f32 v42, v66, v67
	v_cvt_pk_bf16_f32 v43, v68, v69
	s_waitcnt lgkmcnt(1)
	v_mfma_f32_32x32x16_bf16 v[16:31], v[4:7], v[0:3], 0
	ds_read2_b64 v[4:7], v45 offset0:96 offset1:98
	s_and_b32 s0, s0, 0xc0
	s_mov_b64 vcc, s[46:47]
	v_readlane_b32 s1, v254, 36
	s_add_i32 s33, s33, 64
	v_mov_b32_e32 v203, 0
	v_lshl_add_u64 v[192:193], s[2:3], 0, v[98:99]
	v_lshlrev_b64 v[192:193], 9, v[192:193]
	v_lshl_add_u64 v[192:193], vcc, 0, v[192:193]
	s_lshl_b32 s2, s0, 1
	v_lshl_add_u64 v[192:193], v[192:193], 0, s[2:3]
	s_and_b32 s0, s38, 4
	s_or_b32 s0, s0, s1
	s_lshr_b32 s0, s0, 2
	v_lshlrev_b32_e32 v202, 1, v100
	v_lshl_add_u64 v[192:193], v[192:193], 0, v[202:203]
	s_mul_i32 s2, s0, 0x4080
	v_lshl_add_u64 v[194:195], s[2:3], 0, v[98:99]
	s_and_b32 s0, s33, 0xc0
	v_or_b32_e32 v196, s0, v134
	v_lshlrev_b64 v[194:195], 9, v[194:195]
	v_lshl_add_u64 v[194:195], vcc, 0, v[194:195]
	v_lshlrev_b32_e32 v202, 1, v196
	v_lshl_add_u64 v[194:195], v[194:195], 0, v[202:203]
	global_load_dwordx2 v[160:161], v[192:193], off
	global_load_dwordx2 v[162:163], v[192:193], off offset:16
	global_load_dwordx2 v[164:165], v[192:193], off offset:32
	global_load_dwordx2 v[166:167], v[192:193], off offset:48
	global_load_dwordx2 v[168:169], v[192:193], off offset:64
	global_load_dwordx2 v[170:171], v[192:193], off offset:80
	global_load_dwordx2 v[172:173], v[192:193], off offset:96
	global_load_dwordx2 v[174:175], v[192:193], off offset:112
	global_load_dwordx4 v[176:179], v[194:195], off
	global_load_dwordx4 v[180:183], v[194:195], off offset:32
	global_load_dwordx4 v[184:187], v[194:195], off offset:64
	global_load_dwordx4 v[188:191], v[194:195], off offset:96
	v_rcp_f32_e32 v34, v34
	s_waitcnt lgkmcnt(1)
	v_mfma_f32_32x32x16_bf16 v[16:31], v[36:39], v[40:43], v[16:31]
	ds_read2_b64 v[36:39], v45 offset0:100 offset1:102
	s_waitcnt lgkmcnt(1)
	v_mfma_f32_32x32x16_bf16 v[0:15], v[4:7], v[0:3], 0
	s_waitcnt lgkmcnt(0)
	v_mfma_f32_32x32x16_bf16 v[0:15], v[36:39], v[40:43], v[0:15]
	ds_read2_b64 v[40:43], v44 offset0:8 offset1:10
	v_cvt_pk_bf16_f32 v36, v70, v71
	v_cvt_pk_bf16_f32 v37, v72, v73
	v_cvt_pk_bf16_f32 v38, v74, v75
	v_cvt_pk_bf16_f32 v39, v76, v77
	s_waitcnt lgkmcnt(0)
	s_nop 0
	v_mfma_f32_32x32x16_bf16 v[16:31], v[40:43], v[36:39], v[16:31]
	ds_read2_b64 v[40:43], v45 offset0:104 offset1:106
	s_waitcnt lgkmcnt(0)
	v_mfma_f32_32x32x16_bf16 v[0:15], v[40:43], v[36:39], v[0:15]
	ds_read2_b64 v[40:43], v44 offset0:12 offset1:14
	v_cvt_pk_bf16_f32 v36, v83, v81
	v_cvt_pk_bf16_f32 v37, v82, v78
	v_cvt_pk_bf16_f32 v38, v79, v61
	v_cvt_pk_bf16_f32 v39, v62, v59
	s_waitcnt lgkmcnt(0)
	s_nop 0
	v_mfma_f32_32x32x16_bf16 v[16:31], v[40:43], v[36:39], v[16:31]
	ds_read2_b64 v[40:43], v45 offset0:108 offset1:110
	s_waitcnt lgkmcnt(0)
	v_mfma_f32_32x32x16_bf16 v[0:15], v[40:43], v[36:39], v[0:15]
	ds_read2_b64 v[40:43], v44 offset0:16 offset1:18
	v_cvt_pk_bf16_f32 v36, v60, v57
	v_cvt_pk_bf16_f32 v37, v58, v55
	v_cvt_pk_bf16_f32 v38, v56, v53
	v_cvt_pk_bf16_f32 v39, v54, v52
	s_waitcnt lgkmcnt(0)
	s_nop 0
	v_mfma_f32_32x32x16_bf16 v[16:31], v[40:43], v[36:39], v[16:31]
	ds_read2_b64 v[40:43], v45 offset0:112 offset1:114
	s_waitcnt lgkmcnt(0)
	v_mfma_f32_32x32x16_bf16 v[0:15], v[40:43], v[36:39], v[0:15]
	ds_read2_b64 v[40:43], v44 offset0:20 offset1:22
	v_cvt_pk_bf16_f32 v36, v51, v50
	v_cvt_pk_bf16_f32 v37, v49, v48
	v_cvt_pk_bf16_f32 v38, v84, v85
	v_cvt_pk_bf16_f32 v39, v86, v87
	s_waitcnt lgkmcnt(0)
	s_nop 0
	v_mfma_f32_32x32x16_bf16 v[16:31], v[40:43], v[36:39], v[16:31]
	ds_read2_b64 v[40:43], v45 offset0:116 offset1:118
	s_waitcnt lgkmcnt(0)
	v_mfma_f32_32x32x16_bf16 v[0:15], v[40:43], v[36:39], v[0:15]
	ds_read2_b64 v[40:43], v44 offset0:24 offset1:26
	v_cvt_pk_bf16_f32 v36, v88, v89
	v_cvt_pk_bf16_f32 v37, v90, v91
	v_cvt_pk_bf16_f32 v38, v35, v92
	v_cvt_pk_bf16_f32 v39, v33, v32
	s_waitcnt lgkmcnt(0)
	s_nop 0
	v_mfma_f32_32x32x16_bf16 v[16:31], v[40:43], v[36:39], v[16:31]
	ds_read2_b64 v[40:43], v45 offset0:120 offset1:122
	s_waitcnt lgkmcnt(0)
	v_mfma_f32_32x32x16_bf16 v[0:15], v[40:43], v[36:39], v[0:15]
	ds_read2_b64 v[40:43], v44 offset0:28 offset1:30
	v_cvt_pk_bf16_f32 v36, v93, v94
	v_cvt_pk_bf16_f32 v37, v95, v96
	v_cvt_pk_bf16_f32 v38, v137, v138
	v_cvt_pk_bf16_f32 v39, v139, v140
	s_waitcnt lgkmcnt(0)
	s_nop 0
	v_mfma_f32_32x32x16_bf16 v[16:31], v[40:43], v[36:39], v[16:31]
	ds_read2_b64 v[40:43], v45 offset0:124 offset1:126
	s_waitcnt lgkmcnt(0)
	v_mfma_f32_32x32x16_bf16 v[0:15], v[40:43], v[36:39], v[0:15]
	ds_read2_b64 v[40:43], v44 offset0:32 offset1:34
	v_cvt_pk_bf16_f32 v36, v141, v142
	v_cvt_pk_bf16_f32 v37, v143, v144
	v_cvt_pk_bf16_f32 v38, v145, v146
	v_cvt_pk_bf16_f32 v39, v147, v148
	s_waitcnt lgkmcnt(0)
	s_nop 0
	v_mfma_f32_32x32x16_bf16 v[16:31], v[40:43], v[36:39], v[16:31]
	ds_read2_b64 v[40:43], v45 offset0:128 offset1:130
	s_add_u32 s36, s36, 4
	s_addc_u32 s37, s37, 0
	s_mov_b64 s[0:1], 0x80
	s_cmp_eq_u32 s38, 8
	s_waitcnt lgkmcnt(0)
	v_mfma_f32_32x32x16_bf16 v[0:15], v[40:43], v[36:39], v[0:15]
	ds_read2_b64 v[40:43], v44 offset0:36 offset1:38
	v_cvt_pk_bf16_f32 v36, v149, v150
	v_cvt_pk_bf16_f32 v37, v151, v152
	v_cvt_pk_bf16_f32 v38, v153, v154
	v_cvt_pk_bf16_f32 v39, v155, v156
	s_waitcnt lgkmcnt(0)
	s_nop 0
	v_mfma_f32_32x32x16_bf16 v[16:31], v[40:43], v[36:39], v[16:31]
	ds_read2_b64 v[40:43], v45 offset0:132 offset1:134
	s_waitcnt lgkmcnt(0)
	v_mfma_f32_32x32x16_bf16 v[0:15], v[40:43], v[36:39], v[0:15]
	s_nop 0
	s_nop 0
	s_nop 6
	v_pk_mul_f32 v[16:17], v[16:17], v[34:35] op_sel_hi:[1,0]
	v_pk_mul_f32 v[18:19], v[18:19], v[34:35] op_sel_hi:[1,0]
	s_nop 0
	v_pk_mul_f32 v[0:1], v[0:1], v[34:35] op_sel_hi:[1,0]
	v_pk_mul_f32 v[2:3], v[2:3], v[34:35] op_sel_hi:[1,0]
	s_waitcnt vmcnt(11)
	v_lshlrev_b32_e32 v50, 16, v160
	v_and_b32_e32 v51, 0xffff0000, v160
	v_lshlrev_b32_e32 v48, 16, v161
	v_and_b32_e32 v49, 0xffff0000, v161
	v_pk_mul_f32 v[16:17], v[16:17], v[50:51]
	v_pk_mul_f32 v[18:19], v[18:19], v[48:49]
	v_cvt_pk_bf16_f32 v16, v16, v17
	v_cvt_pk_bf16_f32 v17, v18, v19
	global_store_dwordx2 v[102:103], v[16:17], off offset:-64
	v_pk_mul_f32 v[16:17], v[20:21], v[34:35] op_sel_hi:[1,0]
	s_waitcnt vmcnt(11)
	v_lshlrev_b32_e32 v18, 16, v162
	v_and_b32_e32 v19, 0xffff0000, v162
	v_pk_mul_f32 v[16:17], v[16:17], v[18:19]
	v_pk_mul_f32 v[18:19], v[22:23], v[34:35] op_sel_hi:[1,0]
	v_lshlrev_b32_e32 v20, 16, v163
	v_and_b32_e32 v21, 0xffff0000, v163
	v_pk_mul_f32 v[18:19], v[18:19], v[20:21]
	v_cvt_pk_bf16_f32 v16, v16, v17
	v_cvt_pk_bf16_f32 v17, v18, v19
	global_store_dwordx2 v[102:103], v[16:17], off offset:-48
	v_pk_mul_f32 v[16:17], v[24:25], v[34:35] op_sel_hi:[1,0]
	s_waitcnt vmcnt(11)
	v_lshlrev_b32_e32 v18, 16, v164
	v_and_b32_e32 v19, 0xffff0000, v164
	v_pk_mul_f32 v[16:17], v[16:17], v[18:19]
	v_pk_mul_f32 v[18:19], v[26:27], v[34:35] op_sel_hi:[1,0]
	v_lshlrev_b32_e32 v20, 16, v165
	v_and_b32_e32 v21, 0xffff0000, v165
	v_pk_mul_f32 v[18:19], v[18:19], v[20:21]
	v_cvt_pk_bf16_f32 v16, v16, v17
	v_cvt_pk_bf16_f32 v17, v18, v19
	global_store_dwordx2 v[102:103], v[16:17], off offset:-32
	v_pk_mul_f32 v[16:17], v[28:29], v[34:35] op_sel_hi:[1,0]
	s_waitcnt vmcnt(11)
	v_lshlrev_b32_e32 v18, 16, v166
	v_and_b32_e32 v19, 0xffff0000, v166
	v_pk_mul_f32 v[16:17], v[16:17], v[18:19]
	v_pk_mul_f32 v[18:19], v[30:31], v[34:35] op_sel_hi:[1,0]
	v_lshlrev_b32_e32 v20, 16, v167
	v_and_b32_e32 v21, 0xffff0000, v167
	v_pk_mul_f32 v[18:19], v[18:19], v[20:21]
	v_cvt_pk_bf16_f32 v16, v16, v17
	v_cvt_pk_bf16_f32 v17, v18, v19
	global_store_dwordx2 v[102:103], v[16:17], off offset:-16
	s_waitcnt vmcnt(11)
	v_lshlrev_b32_e32 v16, 16, v168
	v_and_b32_e32 v17, 0xffff0000, v168
	v_pk_mul_f32 v[0:1], v[0:1], v[16:17]
	v_lshlrev_b32_e32 v16, 16, v169
	v_and_b32_e32 v17, 0xffff0000, v169
	v_pk_mul_f32 v[2:3], v[2:3], v[16:17]
	v_cvt_pk_bf16_f32 v0, v0, v1
	v_cvt_pk_bf16_f32 v1, v2, v3
	global_store_dwordx2 v[102:103], v[0:1], off
	v_pk_mul_f32 v[0:1], v[4:5], v[34:35] op_sel_hi:[1,0]
	s_waitcnt vmcnt(11)
	v_lshlrev_b32_e32 v2, 16, v170
	v_and_b32_e32 v3, 0xffff0000, v170
	v_pk_mul_f32 v[0:1], v[0:1], v[2:3]
	v_pk_mul_f32 v[2:3], v[6:7], v[34:35] op_sel_hi:[1,0]
	v_lshlrev_b32_e32 v4, 16, v171
	v_and_b32_e32 v5, 0xffff0000, v171
	v_pk_mul_f32 v[2:3], v[2:3], v[4:5]
	v_cvt_pk_bf16_f32 v0, v0, v1
	v_cvt_pk_bf16_f32 v1, v2, v3
	global_store_dwordx2 v[102:103], v[0:1], off offset:16
	v_pk_mul_f32 v[0:1], v[8:9], v[34:35] op_sel_hi:[1,0]
	s_waitcnt vmcnt(11)
	v_lshlrev_b32_e32 v2, 16, v172
	v_and_b32_e32 v3, 0xffff0000, v172
	v_pk_mul_f32 v[0:1], v[0:1], v[2:3]
	v_pk_mul_f32 v[2:3], v[10:11], v[34:35] op_sel_hi:[1,0]
	v_lshlrev_b32_e32 v4, 16, v173
	v_and_b32_e32 v5, 0xffff0000, v173
	v_pk_mul_f32 v[2:3], v[2:3], v[4:5]
	v_cvt_pk_bf16_f32 v0, v0, v1
	v_cvt_pk_bf16_f32 v1, v2, v3
	global_store_dwordx2 v[102:103], v[0:1], off offset:32
	v_pk_mul_f32 v[0:1], v[12:13], v[34:35] op_sel_hi:[1,0]
	s_waitcnt vmcnt(11)
	v_lshlrev_b32_e32 v2, 16, v174
	v_and_b32_e32 v3, 0xffff0000, v174
	v_pk_mul_f32 v[0:1], v[0:1], v[2:3]
	v_pk_mul_f32 v[2:3], v[14:15], v[34:35] op_sel_hi:[1,0]
	v_lshlrev_b32_e32 v4, 16, v175
	v_and_b32_e32 v5, 0xffff0000, v175
	v_pk_mul_f32 v[2:3], v[2:3], v[4:5]
	v_cvt_pk_bf16_f32 v0, v0, v1
	v_cvt_pk_bf16_f32 v1, v2, v3
	global_store_dwordx2 v[102:103], v[0:1], off offset:48
	v_lshl_add_u64 v[102:103], v[102:103], 0, s[0:1]
	s_waitcnt vmcnt(8)
	v_mov_b32_e32 v80, v176
	v_mov_b32_e32 v81, v177
	v_mov_b32_e32 v82, v178
	v_mov_b32_e32 v83, v179
	v_mov_b32_e32 v84, v180
	v_mov_b32_e32 v85, v181
	v_mov_b32_e32 v86, v182
	v_mov_b32_e32 v87, v183
	v_mov_b32_e32 v88, v184
	v_mov_b32_e32 v89, v185
	v_mov_b32_e32 v90, v186
	v_mov_b32_e32 v91, v187
	v_mov_b32_e32 v92, v188
	v_mov_b32_e32 v93, v189
	v_mov_b32_e32 v94, v190
	v_mov_b32_e32 v95, v191
	s_cbranch_scc0 .LBB0_2056
	v_readlane_b32 s91, v254, 17
	v_readlane_b32 s24, v254, 52
	s_mov_b32 s37, s3
	s_movk_i32 s25, 0x90
	s_branch .LBB0_1999
